# scan: B1 wait counted vmcnt(6), others drained
# baseline (speedup 1.0000x reference)
.Lsc_step:
	ds_read_b128 v[212:215], v2
	ds_read_b128 v[216:219], v2 offset:4096
	ds_read_b128 v[220:223], v2 offset:8192
	ds_read_b128 v[224:227], v2 offset:12288
	ds_read_b128 v[228:231], v2 offset:1024
	ds_read2st64_b64 v[188:191], v131 offset0:112 offset1:113
	ds_read2st64_b64 v[192:195], v131 offset0:114 offset1:115
	v_cvt_pk_bf16_f32 v132, v16, v17
	v_cvt_pk_bf16_f32 v133, v18, v19
	v_cvt_pk_bf16_f32 v134, v4, v5
	v_cvt_pk_bf16_f32 v135, v6, v7
	v_cvt_pk_bf16_f32 v136, v44, v45
	v_cvt_pk_bf16_f32 v137, v46, v47
	v_cvt_pk_bf16_f32 v138, v76, v77
	v_cvt_pk_bf16_f32 v139, v78, v79
	v_cvt_pk_bf16_f32 v140, v84, v85
	v_cvt_pk_bf16_f32 v141, v86, v87
	v_cvt_pk_bf16_f32 v142, v88, v89
	v_cvt_pk_bf16_f32 v143, v90, v91
	v_cvt_pk_bf16_f32 v144, v92, v93
	v_cvt_pk_bf16_f32 v145, v94, v95
	v_cvt_pk_bf16_f32 v146, v96, v97
	v_cvt_pk_bf16_f32 v147, v98, v99
	v_add_u32_e32 v197, 0x4000c00, v114
	s_waitcnt lgkmcnt(6)
	v_mfma_f32_16x16x32_bf16 v[156:159], v[212:215], v[132:135], 0
	ds_read_b128 v[232:235], v2 offset:5120
	s_waitcnt lgkmcnt(6)
	v_mfma_f32_16x16x32_bf16 v[160:163], v[216:219], v[132:135], 0
	ds_read_b128 v[236:239], v2 offset:9216
	s_waitcnt lgkmcnt(6)
	v_mfma_f32_16x16x32_bf16 v[164:167], v[220:223], v[132:135], 0
	ds_read_b128 v[212:215], v2 offset:13312
	s_waitcnt lgkmcnt(6)
	v_mfma_f32_16x16x32_bf16 v[168:171], v[224:227], v[132:135], 0
	ds_read_b128 v[216:219], v2 offset:2048
	s_waitcnt lgkmcnt(6)
	v_mfma_f32_16x16x32_bf16 v[156:159], v[228:231], v[136:139], v[156:159]
	ds_read_b128 v[220:223], v2 offset:6144
	s_waitcnt lgkmcnt(4)
	v_mfma_f32_16x16x32_bf16 v[160:163], v[232:235], v[136:139], v[160:163]
	ds_read_b128 v[224:227], v2 offset:10240
	s_waitcnt lgkmcnt(4)
	v_mfma_f32_16x16x32_bf16 v[164:167], v[236:239], v[136:139], v[164:167]
	ds_read_b128 v[228:231], v2 offset:14336
	s_waitcnt lgkmcnt(4)
	v_mfma_f32_16x16x32_bf16 v[168:171], v[212:215], v[136:139], v[168:171]
	ds_read_b128 v[232:235], v2 offset:3072
	s_waitcnt lgkmcnt(4)
	v_mfma_f32_16x16x32_bf16 v[156:159], v[216:219], v[140:143], v[156:159]
	ds_read_b128 v[236:239], v2 offset:7168
	s_waitcnt lgkmcnt(4)
	v_mfma_f32_16x16x32_bf16 v[160:163], v[220:223], v[140:143], v[160:163]
	ds_read_b128 v[212:215], v2 offset:11264
	s_waitcnt lgkmcnt(4)
	v_mfma_f32_16x16x32_bf16 v[164:167], v[224:227], v[140:143], v[164:167]
	ds_read_b128 v[216:219], v2 offset:15360
	s_waitcnt lgkmcnt(4)
	v_mfma_f32_16x16x32_bf16 v[168:171], v[228:231], v[140:143], v[168:171]
	s_waitcnt lgkmcnt(3)
	v_mfma_f32_16x16x32_bf16 v[156:159], v[232:235], v[144:147], v[156:159]
	s_waitcnt lgkmcnt(2)
	v_mfma_f32_16x16x32_bf16 v[160:163], v[236:239], v[144:147], v[160:163]
	s_waitcnt lgkmcnt(1)
	v_mfma_f32_16x16x32_bf16 v[164:167], v[212:215], v[144:147], v[164:167]
	s_waitcnt lgkmcnt(0)
	v_mfma_f32_16x16x32_bf16 v[168:171], v[216:219], v[144:147], v[168:171]
	s_waitcnt lgkmcnt(0)
	s_waitcnt vmcnt(6)
	s_barrier
	s_cmp_eq_u32 s6, 0
	s_cbranch_scc1 .Lsc_skip1
	s_mov_b32 m0, s88
	s_nop 0
	global_load_lds_dwordx4 v[8:9], off
	s_add_i32 m0, s88, 0x400
	v_lshl_add_u64 v[30:31], v[8:9], 0, s[78:79]
	global_load_lds_dwordx4 v[30:31], off
	s_add_i32 m0, s88, 0x800
	v_lshl_add_u64 v[30:31], v[8:9], 0, s[98:99]
	global_load_lds_dwordx4 v[30:31], off
	s_add_i32 m0, s88, 0xc00
	v_lshl_add_u64 v[30:31], v[8:9], 0, s[100:101]
	global_load_lds_dwordx4 v[30:31], off
	s_mov_b32 m0, s92
	s_nop 0
	global_load_lds_dwordx4 v[20:21], off
	s_add_i32 m0, s92, 0x400
	v_lshl_add_u64 v[30:31], v[20:21], 0, s[78:79]
	global_load_lds_dwordx4 v[30:31], off
